# XCD-aware NA item order on top of the pipelined NA loop (items sharing K/V rows on one XCD)
# baseline (speedup 1.0000x reference)
.LBB0_504:
	s_and_b32 s28, s29, 0xffffff03
	s_lshr_b32 s0, s29, 1
	s_and_b32 s0, s0, 0x7c
	s_or_b32 s28, s28, s0
	s_and_b32 s0, s29, 4
	s_lshl_b32 s0, s0, 5
	s_or_b32 s28, s28, s0
	s_ashr_i32 s0, s28, 4
	s_cmpk_gt_i32 s0, 0x7f
	s_mov_b64 s[8:9], -1
	s_cbranch_scc0 .LBB0_506
	s_lshl_b32 s6, s0, 9
	s_add_i32 s6, s6, 0x7fff0000
	s_and_b32 s6, s6, 0x7fffe000
	s_add_i32 s6, s6, 0x10000
	s_mov_b64 s[8:9], 0
.LBB0_506:
	s_andn2_b64 vcc, exec, s[8:9]
	s_cbranch_vccnz .LBB0_508
	s_lshl_b32 s6, s28, 5
	s_and_b32 s6, s6, 0xfffff000
	s_mov_b32 s18, 56
	s_mov_b32 s7, 7
	s_bfe_u32 s19, s28, 0x20002
	s_cmp_lt_i32 s19, 1
	s_mov_b32 s8, s19
	s_cbranch_scc0 .LBB0_509
	s_branch .LBB0_513
.LBB0_508:
	s_movk_i32 s18, 0x78
	s_mov_b32 s7, 15
	s_bfe_u32 s19, s28, 0x20002
	s_cmp_lt_i32 s19, 1
	s_mov_b32 s8, s19
	s_cbranch_scc1 .LBB0_513

.LBB0_513:
	s_and_b32 s9, s28, 3
	s_and_b32 s0, s7, s0
	s_lshl_b32 s17, s0, 3
	s_add_i32 s7, s17, -4
	s_min_i32 s7, s7, s18
	s_cmp_lg_u32 s0, 0
	s_cselect_b32 s16, s7, 0
	s_or_b32 s0, s17, 3
	s_min_u32 s0, s0, s18
	s_sub_i32 s7, s0, s16
	s_add_i32 s7, s7, 8
	s_movk_i32 s79, 0x88
	v_readfirstlane_b32 s10, v195
	s_nop 0
	s_lshr_b32 s11, s10, 8
	s_lshr_b32 s10, s10, 6
	s_sub_i32 s0, s7, s11
	s_branch .Lna_L
